# P4 and P8 prompt-panel residual epilogues: gate loaded once, residual loads 3 row-groups deep (all 6 residual epilogue sites hand-pipelined)
# baseline (speedup 1.0000x reference)
;     static __device__ __forceinline__ const void* rowptr(const void* b, size_t r, int ldc) { if constexpr (BASE_BF16) return (const bf16_t*)b + r * ldc; else return (const float*)b + r * ldc; }
;     static __device__ __forceinline__ void stq(bf16_t* p, f32x4 v) { u32x2 w; w.x = cvt_pk_bf16(v[0], v[1]); w.y = cvt_pk_bf16(v[2], v[3]); *(u32x2*)p = w; }
;     __device__ __forceinline__ void operator()(const f32x4 (&acc)[2][2][4][2], const Unit& u, int wr, int wc, int fr, int fq) const {
;     ...
;         if (PIPE && u.pm * BM < split_rows) {
;             f32x4 gq[2][2], bc[2][2], bn[2][2];
;             { const void* rp = rowptr(base_p, (size_t)(u.pm * BM + wr * 64 + fr), ldc);
; #pragma unroll
;             for (int bj = 0; bj < 2; ++bj)
; #pragma unroll
;                 for (int n = 0; n < 2; ++n) { gq[bj][n] = *(const f32x4*)(mod + goff + col0 + bj * HALF + n * 16) * gs; bc[bj][n] = ldb(rp, col0 + bj * HALF + n * 16); } }
; #pragma unroll
;             for (int gi = 0; gi < 8; ++gi) { const int ai = gi >> 2, m = gi & 3; const int r = u.pm * BM + ai * HALF + wr * 64 + m * 16 + fr;
;                 if (gi < 7) { const void* rp = rowptr(base_p, (size_t)(u.pm * BM + ((gi + 1) >> 2) * HALF + wr * 64 + ((gi + 1) & 3) * 16 + fr), ldc);
; #pragma unroll
;                     for (int bj = 0; bj < 2; ++bj)
; #pragma unroll
;                         for (int n = 0; n < 2; ++n) bn[bj][n] = ldb(rp, col0 + bj * HALF + n * 16); }
;                 bf16_t* orow = out + (size_t)r * ldc;
; #pragma unroll
;                 for (int bj = 0; bj < 2; ++bj)
; #pragma unroll
;                     for (int n = 0; n < 2; ++n) { stq(orow + col0 + bj * HALF + n * 16, bc[bj][n] + gq[bj][n] * acc[ai][bj][m][n]); bc[bj][n] = bn[bj][n]; }
;                 asm volatile("" ::: "memory"); }
.LBB0_345:
	s_add_u32 s38, s56, 0x8000
	s_addc_u32 s39, s57, 0
	v_lshlrev_b32_e32 v3, 2, v2
	v_lshlrev_b32_e32 v16, 1, v2
	v_lshl_add_u32 v16, v18, 13, v16
	global_load_dwordx4 v[180:183], v3, s[38:39]
	global_load_dwordx4 v[184:187], v3, s[38:39] offset:64
	global_load_dwordx4 v[188:191], v3, s[38:39] offset:512
	global_load_dwordx4 v[192:195], v3, s[38:39] offset:576
	v_mov_b32_e32 v19, v16
	v_lshlrev_b32_e32 v19, 1, v19
	global_load_dwordx4 v[204:207], v19, s[52:53]
	global_load_dwordx4 v[208:211], v19, s[52:53] offset:64
	global_load_dwordx4 v[212:215], v19, s[52:53] offset:512
	global_load_dwordx4 v[216:219], v19, s[52:53] offset:576
	v_add_u32_e32 v19, 0x20000, v16
	v_lshlrev_b32_e32 v19, 1, v19
	global_load_dwordx4 v[220:223], v19, s[52:53]
	global_load_dwordx4 v[224:227], v19, s[52:53] offset:64
	global_load_dwordx4 v[228:231], v19, s[52:53] offset:512
	global_load_dwordx4 v[232:235], v19, s[52:53] offset:576
	v_add_u32_e32 v19, 0x40000, v16
	v_lshlrev_b32_e32 v19, 1, v19
	global_load_dwordx4 v[236:239], v19, s[52:53]
	global_load_dwordx4 v[240:243], v19, s[52:53] offset:64
	global_load_dwordx4 v[244:247], v19, s[52:53] offset:512
	global_load_dwordx4 v[248:251], v19, s[52:53] offset:576
	s_waitcnt vmcnt(8)
	v_pk_mul_f32 v[180:181], v[180:181], s[20:21] op_sel_hi:[1,0]
	v_pk_mul_f32 v[182:183], v[182:183], s[20:21] op_sel_hi:[1,0]
	v_pk_mul_f32 v[184:185], v[184:185], s[20:21] op_sel_hi:[1,0]
	v_pk_mul_f32 v[186:187], v[186:187], s[20:21] op_sel_hi:[1,0]
	v_pk_mul_f32 v[188:189], v[188:189], s[20:21] op_sel_hi:[1,0]
	v_pk_mul_f32 v[190:191], v[190:191], s[20:21] op_sel_hi:[1,0]
	v_pk_mul_f32 v[192:193], v[192:193], s[20:21] op_sel_hi:[1,0]
	v_pk_mul_f32 v[194:195], v[194:195], s[20:21] op_sel_hi:[1,0]
	v_mov_b32_e32 v20, v16
	v_pk_fma_f32 v[204:205], v[180:181], v[158:159], v[204:205]
	v_pk_fma_f32 v[206:207], v[182:183], v[160:161], v[206:207]
	v_cvt_pk_bf16_f32 v22, v204, v205
	v_cvt_pk_bf16_f32 v23, v206, v207
	global_store_dwordx2 v20, v[22:23], s[68:69]
	v_pk_fma_f32 v[208:209], v[184:185], v[154:155], v[208:209]
	v_pk_fma_f32 v[210:211], v[186:187], v[156:157], v[210:211]
	v_cvt_pk_bf16_f32 v22, v208, v209
	v_cvt_pk_bf16_f32 v23, v210, v211
	global_store_dwordx2 v20, v[22:23], s[68:69] offset:32
	v_pk_fma_f32 v[212:213], v[188:189], v[150:151], v[212:213]
	v_pk_fma_f32 v[214:215], v[190:191], v[152:153], v[214:215]
	v_cvt_pk_bf16_f32 v22, v212, v213
	v_cvt_pk_bf16_f32 v23, v214, v215
	global_store_dwordx2 v20, v[22:23], s[68:69] offset:256
	v_pk_fma_f32 v[216:217], v[192:193], v[146:147], v[216:217]
	v_pk_fma_f32 v[218:219], v[194:195], v[148:149], v[218:219]
	v_cvt_pk_bf16_f32 v22, v216, v217
	v_cvt_pk_bf16_f32 v23, v218, v219
	global_store_dwordx2 v20, v[22:23], s[68:69] offset:288
	v_add_u32_e32 v19, 0x60000, v16
	v_lshlrev_b32_e32 v19, 1, v19
	global_load_dwordx4 v[204:207], v19, s[52:53]
	global_load_dwordx4 v[208:211], v19, s[52:53] offset:64
	global_load_dwordx4 v[212:215], v19, s[52:53] offset:512
	global_load_dwordx4 v[216:219], v19, s[52:53] offset:576
	s_waitcnt vmcnt(12)
	v_add_u32_e32 v20, 0x20000, v16
	v_pk_fma_f32 v[220:221], v[180:181], v[142:143], v[220:221]
	v_pk_fma_f32 v[222:223], v[182:183], v[144:145], v[222:223]
	v_cvt_pk_bf16_f32 v22, v220, v221
	v_cvt_pk_bf16_f32 v23, v222, v223
	global_store_dwordx2 v20, v[22:23], s[68:69]
	v_pk_fma_f32 v[224:225], v[184:185], v[138:139], v[224:225]
	v_pk_fma_f32 v[226:227], v[186:187], v[140:141], v[226:227]
	v_cvt_pk_bf16_f32 v22, v224, v225
	v_cvt_pk_bf16_f32 v23, v226, v227
	global_store_dwordx2 v20, v[22:23], s[68:69] offset:32
	v_pk_fma_f32 v[228:229], v[188:189], v[134:135], v[228:229]
	v_pk_fma_f32 v[230:231], v[190:191], v[136:137], v[230:231]
	v_cvt_pk_bf16_f32 v22, v228, v229
	v_cvt_pk_bf16_f32 v23, v230, v231
	global_store_dwordx2 v20, v[22:23], s[68:69] offset:256
	v_pk_fma_f32 v[232:233], v[192:193], v[130:131], v[232:233]
	v_pk_fma_f32 v[234:235], v[194:195], v[132:133], v[234:235]
	v_cvt_pk_bf16_f32 v22, v232, v233
	v_cvt_pk_bf16_f32 v23, v234, v235
	global_store_dwordx2 v20, v[22:23], s[68:69] offset:288
	v_add_u32_e32 v19, 0x100000, v16
	v_lshlrev_b32_e32 v19, 1, v19
	global_load_dwordx4 v[220:223], v19, s[52:53]
	global_load_dwordx4 v[224:227], v19, s[52:53] offset:64
	global_load_dwordx4 v[228:231], v19, s[52:53] offset:512
	global_load_dwordx4 v[232:235], v19, s[52:53] offset:576
	s_waitcnt vmcnt(16)
	v_add_u32_e32 v20, 0x40000, v16
	v_pk_fma_f32 v[236:237], v[180:181], v[126:127], v[236:237]
	v_pk_fma_f32 v[238:239], v[182:183], v[128:129], v[238:239]
	v_cvt_pk_bf16_f32 v22, v236, v237
	v_cvt_pk_bf16_f32 v23, v238, v239
	global_store_dwordx2 v20, v[22:23], s[68:69]
	v_pk_fma_f32 v[240:241], v[184:185], v[122:123], v[240:241]
	v_pk_fma_f32 v[242:243], v[186:187], v[124:125], v[242:243]
	v_cvt_pk_bf16_f32 v22, v240, v241
	v_cvt_pk_bf16_f32 v23, v242, v243
	global_store_dwordx2 v20, v[22:23], s[68:69] offset:32
	v_pk_fma_f32 v[244:245], v[188:189], v[118:119], v[244:245]
	v_pk_fma_f32 v[246:247], v[190:191], v[120:121], v[246:247]
	v_cvt_pk_bf16_f32 v22, v244, v245
	v_cvt_pk_bf16_f32 v23, v246, v247
	global_store_dwordx2 v20, v[22:23], s[68:69] offset:256
	v_pk_fma_f32 v[248:249], v[192:193], v[114:115], v[248:249]
	v_pk_fma_f32 v[250:251], v[194:195], v[116:117], v[250:251]
	v_cvt_pk_bf16_f32 v22, v248, v249
	v_cvt_pk_bf16_f32 v23, v250, v251
	global_store_dwordx2 v20, v[22:23], s[68:69] offset:288
	v_add_u32_e32 v19, 0x120000, v16
	v_lshlrev_b32_e32 v19, 1, v19
	global_load_dwordx4 v[236:239], v19, s[52:53]
	global_load_dwordx4 v[240:243], v19, s[52:53] offset:64
	global_load_dwordx4 v[244:247], v19, s[52:53] offset:512
	global_load_dwordx4 v[248:251], v19, s[52:53] offset:576
	s_waitcnt vmcnt(16)
;     static __device__ __forceinline__ const void* rowptr(const void* b, size_t r, int ldc) { if constexpr (BASE_BF16) return (const bf16_t*)b + r * ldc; else return (const float*)b + r * ldc; }
;     static __device__ __forceinline__ void stq(bf16_t* p, f32x4 v) { u32x2 w; w.x = cvt_pk_bf16(v[0], v[1]); w.y = cvt_pk_bf16(v[2], v[3]); *(u32x2*)p = w; }
;     __device__ __forceinline__ void operator()(const f32x4 (&acc)[2][2][4][2], const Unit& u, int wr, int wc, int fr, int fq) const {
;     ...
;         if (PIPE && u.pm * BM < split_rows) {
;             f32x4 gq[2][2], bc[2][2], bn[2][2];
;             { const void* rp = rowptr(base_p, (size_t)(u.pm * BM + wr * 64 + fr), ldc);
; #pragma unroll
;             for (int bj = 0; bj < 2; ++bj)
; #pragma unroll
;                 for (int n = 0; n < 2; ++n) { gq[bj][n] = *(const f32x4*)(mod + goff + col0 + bj * HALF + n * 16) * gs; bc[bj][n] = ldb(rp, col0 + bj * HALF + n * 16); } }
; #pragma unroll
;             for (int gi = 0; gi < 8; ++gi) { const int ai = gi >> 2, m = gi & 3; const int r = u.pm * BM + ai * HALF + wr * 64 + m * 16 + fr;
;                 if (gi < 7) { const void* rp = rowptr(base_p, (size_t)(u.pm * BM + ((gi + 1) >> 2) * HALF + wr * 64 + ((gi + 1) & 3) * 16 + fr), ldc);
; #pragma unroll
;                     for (int bj = 0; bj < 2; ++bj)
; #pragma unroll
;                         for (int n = 0; n < 2; ++n) bn[bj][n] = ldb(rp, col0 + bj * HALF + n * 16); }
;                 bf16_t* orow = out + (size_t)r * ldc;
; #pragma unroll
;                 for (int bj = 0; bj < 2; ++bj)
; #pragma unroll
;                     for (int n = 0; n < 2; ++n) { stq(orow + col0 + bj * HALF + n * 16, bc[bj][n] + gq[bj][n] * acc[ai][bj][m][n]); bc[bj][n] = bn[bj][n]; }
;                 asm volatile("" ::: "memory"); }
	v_add_u32_e32 v20, 0x60000, v16
	v_pk_fma_f32 v[204:205], v[180:181], v[110:111], v[204:205]
	v_pk_fma_f32 v[206:207], v[182:183], v[112:113], v[206:207]
	v_cvt_pk_bf16_f32 v22, v204, v205
	v_cvt_pk_bf16_f32 v23, v206, v207
	global_store_dwordx2 v20, v[22:23], s[68:69]
	v_pk_fma_f32 v[208:209], v[184:185], v[106:107], v[208:209]
	v_pk_fma_f32 v[210:211], v[186:187], v[108:109], v[210:211]
	v_cvt_pk_bf16_f32 v22, v208, v209
	v_cvt_pk_bf16_f32 v23, v210, v211
	global_store_dwordx2 v20, v[22:23], s[68:69] offset:32
	v_pk_fma_f32 v[212:213], v[188:189], v[102:103], v[212:213]
	v_pk_fma_f32 v[214:215], v[190:191], v[104:105], v[214:215]
	v_cvt_pk_bf16_f32 v22, v212, v213
	v_cvt_pk_bf16_f32 v23, v214, v215
	global_store_dwordx2 v20, v[22:23], s[68:69] offset:256
	v_pk_fma_f32 v[216:217], v[192:193], v[98:99], v[216:217]
	v_pk_fma_f32 v[218:219], v[194:195], v[100:101], v[218:219]
	v_cvt_pk_bf16_f32 v22, v216, v217
	v_cvt_pk_bf16_f32 v23, v218, v219
	global_store_dwordx2 v20, v[22:23], s[68:69] offset:288
	v_add_u32_e32 v19, 0x140000, v16
	v_lshlrev_b32_e32 v19, 1, v19
	global_load_dwordx4 v[204:207], v19, s[52:53]
	global_load_dwordx4 v[208:211], v19, s[52:53] offset:64
	global_load_dwordx4 v[212:215], v19, s[52:53] offset:512
	global_load_dwordx4 v[216:219], v19, s[52:53] offset:576
	s_waitcnt vmcnt(16)
	v_add_u32_e32 v20, 0x100000, v16
	v_pk_fma_f32 v[220:221], v[180:181], v[94:95], v[220:221]
	v_pk_fma_f32 v[222:223], v[182:183], v[96:97], v[222:223]
	v_cvt_pk_bf16_f32 v22, v220, v221
	v_cvt_pk_bf16_f32 v23, v222, v223
	global_store_dwordx2 v20, v[22:23], s[68:69]
	v_pk_fma_f32 v[224:225], v[184:185], v[90:91], v[224:225]
	v_pk_fma_f32 v[226:227], v[186:187], v[92:93], v[226:227]
	v_cvt_pk_bf16_f32 v22, v224, v225
	v_cvt_pk_bf16_f32 v23, v226, v227
	global_store_dwordx2 v20, v[22:23], s[68:69] offset:32
	v_pk_fma_f32 v[228:229], v[188:189], v[86:87], v[228:229]
	v_pk_fma_f32 v[230:231], v[190:191], v[88:89], v[230:231]
	v_cvt_pk_bf16_f32 v22, v228, v229
	v_cvt_pk_bf16_f32 v23, v230, v231
	global_store_dwordx2 v20, v[22:23], s[68:69] offset:256
	v_pk_fma_f32 v[232:233], v[192:193], v[82:83], v[232:233]
	v_pk_fma_f32 v[234:235], v[194:195], v[84:85], v[234:235]
	v_cvt_pk_bf16_f32 v22, v232, v233
	v_cvt_pk_bf16_f32 v23, v234, v235
	global_store_dwordx2 v20, v[22:23], s[68:69] offset:288
	v_add_u32_e32 v19, 0x160000, v16
	v_lshlrev_b32_e32 v19, 1, v19
	global_load_dwordx4 v[220:223], v19, s[52:53]
	global_load_dwordx4 v[224:227], v19, s[52:53] offset:64
	global_load_dwordx4 v[228:231], v19, s[52:53] offset:512
	global_load_dwordx4 v[232:235], v19, s[52:53] offset:576
	s_waitcnt vmcnt(16)
	v_add_u32_e32 v20, 0x120000, v16
	v_pk_fma_f32 v[236:237], v[180:181], v[78:79], v[236:237]
	v_pk_fma_f32 v[238:239], v[182:183], v[80:81], v[238:239]
	v_cvt_pk_bf16_f32 v22, v236, v237
	v_cvt_pk_bf16_f32 v23, v238, v239
	global_store_dwordx2 v20, v[22:23], s[68:69]
	v_pk_fma_f32 v[240:241], v[184:185], v[74:75], v[240:241]
	v_pk_fma_f32 v[242:243], v[186:187], v[76:77], v[242:243]
	v_cvt_pk_bf16_f32 v22, v240, v241
	v_cvt_pk_bf16_f32 v23, v242, v243
	global_store_dwordx2 v20, v[22:23], s[68:69] offset:32
	v_pk_fma_f32 v[244:245], v[188:189], v[70:71], v[244:245]
	v_pk_fma_f32 v[246:247], v[190:191], v[72:73], v[246:247]
	v_cvt_pk_bf16_f32 v22, v244, v245
	v_cvt_pk_bf16_f32 v23, v246, v247
	global_store_dwordx2 v20, v[22:23], s[68:69] offset:256
	v_pk_fma_f32 v[248:249], v[192:193], v[66:67], v[248:249]
	v_pk_fma_f32 v[250:251], v[194:195], v[68:69], v[250:251]
	v_cvt_pk_bf16_f32 v22, v248, v249
	v_cvt_pk_bf16_f32 v23, v250, v251
	global_store_dwordx2 v20, v[22:23], s[68:69] offset:288
	s_waitcnt vmcnt(12)
	v_add_u32_e32 v20, 0x140000, v16
	v_pk_fma_f32 v[204:205], v[180:181], v[62:63], v[204:205]
	v_pk_fma_f32 v[206:207], v[182:183], v[64:65], v[206:207]
	v_cvt_pk_bf16_f32 v22, v204, v205
	v_cvt_pk_bf16_f32 v23, v206, v207
	global_store_dwordx2 v20, v[22:23], s[68:69]
	v_pk_fma_f32 v[208:209], v[184:185], v[58:59], v[208:209]
	v_pk_fma_f32 v[210:211], v[186:187], v[60:61], v[210:211]
	v_cvt_pk_bf16_f32 v22, v208, v209
	v_cvt_pk_bf16_f32 v23, v210, v211
	global_store_dwordx2 v20, v[22:23], s[68:69] offset:32
	v_pk_fma_f32 v[212:213], v[188:189], v[54:55], v[212:213]
	v_pk_fma_f32 v[214:215], v[190:191], v[56:57], v[214:215]
	v_cvt_pk_bf16_f32 v22, v212, v213
	v_cvt_pk_bf16_f32 v23, v214, v215
	global_store_dwordx2 v20, v[22:23], s[68:69] offset:256
	v_pk_fma_f32 v[216:217], v[192:193], v[50:51], v[216:217]
	v_pk_fma_f32 v[218:219], v[194:195], v[52:53], v[218:219]
	v_cvt_pk_bf16_f32 v22, v216, v217
	v_cvt_pk_bf16_f32 v23, v218, v219
	global_store_dwordx2 v20, v[22:23], s[68:69] offset:288
	s_waitcnt vmcnt(8)
	v_add_u32_e32 v20, 0x160000, v16
	v_pk_fma_f32 v[220:221], v[180:181], v[46:47], v[220:221]
	v_pk_fma_f32 v[222:223], v[182:183], v[48:49], v[222:223]
	v_cvt_pk_bf16_f32 v22, v220, v221
	v_cvt_pk_bf16_f32 v23, v222, v223
	global_store_dwordx2 v20, v[22:23], s[68:69]
	v_pk_fma_f32 v[224:225], v[184:185], v[42:43], v[224:225]
	v_pk_fma_f32 v[226:227], v[186:187], v[44:45], v[226:227]
	v_cvt_pk_bf16_f32 v22, v224, v225
	v_cvt_pk_bf16_f32 v23, v226, v227
	global_store_dwordx2 v20, v[22:23], s[68:69] offset:32
	v_pk_fma_f32 v[228:229], v[188:189], v[38:39], v[228:229]
	v_pk_fma_f32 v[230:231], v[190:191], v[40:41], v[230:231]
	v_cvt_pk_bf16_f32 v22, v228, v229
	v_cvt_pk_bf16_f32 v23, v230, v231
	global_store_dwordx2 v20, v[22:23], s[68:69] offset:256
	v_pk_fma_f32 v[232:233], v[192:193], v[34:35], v[232:233]
	v_pk_fma_f32 v[234:235], v[194:195], v[36:37], v[234:235]
	v_cvt_pk_bf16_f32 v22, v232, v233
	v_cvt_pk_bf16_f32 v23, v234, v235
	global_store_dwordx2 v20, v[22:23], s[68:69] offset:288
	s_and_b64 vcc, exec, s[2:3]
	s_mov_b64 s[2:3], -1
	s_cbranch_vccnz .LBB0_298

;     static __device__ __forceinline__ const void* rowptr(const void* b, size_t r, int ldc) { if constexpr (BASE_BF16) return (const bf16_t*)b + r * ldc; else return (const float*)b + r * ldc; }
;     static __device__ __forceinline__ void stq(bf16_t* p, f32x4 v) { u32x2 w; w.x = cvt_pk_bf16(v[0], v[1]); w.y = cvt_pk_bf16(v[2], v[3]); *(u32x2*)p = w; }
;     __device__ __forceinline__ void operator()(const f32x4 (&acc)[2][2][4][2], const Unit& u, int wr, int wc, int fr, int fq) const {
;     ...
;         if (PIPE && u.pm * BM < split_rows) {
;             f32x4 gq[2][2], bc[2][2], bn[2][2];
;             { const void* rp = rowptr(base_p, (size_t)(u.pm * BM + wr * 64 + fr), ldc);
; #pragma unroll
;             for (int bj = 0; bj < 2; ++bj)
; #pragma unroll
;                 for (int n = 0; n < 2; ++n) { gq[bj][n] = *(const f32x4*)(mod + goff + col0 + bj * HALF + n * 16) * gs; bc[bj][n] = ldb(rp, col0 + bj * HALF + n * 16); } }
; #pragma unroll
;             for (int gi = 0; gi < 8; ++gi) { const int ai = gi >> 2, m = gi & 3; const int r = u.pm * BM + ai * HALF + wr * 64 + m * 16 + fr;
;                 if (gi < 7) { const void* rp = rowptr(base_p, (size_t)(u.pm * BM + ((gi + 1) >> 2) * HALF + wr * 64 + ((gi + 1) & 3) * 16 + fr), ldc);
; #pragma unroll
;                     for (int bj = 0; bj < 2; ++bj)
; #pragma unroll
;                         for (int n = 0; n < 2; ++n) bn[bj][n] = ldb(rp, col0 + bj * HALF + n * 16); }
;                 bf16_t* orow = out + (size_t)r * ldc;
; #pragma unroll
;                 for (int bj = 0; bj < 2; ++bj)
; #pragma unroll
;                     for (int n = 0; n < 2; ++n) { stq(orow + col0 + bj * HALF + n * 16, bc[bj][n] + gq[bj][n] * acc[ai][bj][m][n]); bc[bj][n] = bn[bj][n]; }
;                 asm volatile("" ::: "memory"); }
.LBB0_764:
	s_add_u32 s60, s56, s20
	s_addc_u32 s61, s57, s21
	v_lshlrev_b32_e32 v131, 2, v130
	v_lshlrev_b32_e32 v132, 1, v130
	v_lshl_add_u32 v132, v160, 13, v132
	global_load_dwordx4 v[180:183], v131, s[60:61]
	global_load_dwordx4 v[184:187], v131, s[60:61] offset:64
	global_load_dwordx4 v[188:191], v131, s[60:61] offset:512
	global_load_dwordx4 v[192:195], v131, s[60:61] offset:576
	v_mov_b32_e32 v133, v132
	global_load_dwordx2 v[196:197], v133, s[68:69]
	global_load_dwordx2 v[198:199], v133, s[68:69] offset:32
	global_load_dwordx2 v[200:201], v133, s[68:69] offset:256
	global_load_dwordx2 v[202:203], v133, s[68:69] offset:288
	v_add_u32_e32 v133, 0x20000, v132
	global_load_dwordx2 v[204:205], v133, s[68:69]
	global_load_dwordx2 v[206:207], v133, s[68:69] offset:32
	global_load_dwordx2 v[208:209], v133, s[68:69] offset:256
	global_load_dwordx2 v[210:211], v133, s[68:69] offset:288
	v_add_u32_e32 v133, 0x40000, v132
	global_load_dwordx2 v[212:213], v133, s[68:69]
	global_load_dwordx2 v[214:215], v133, s[68:69] offset:32
	global_load_dwordx2 v[216:217], v133, s[68:69] offset:256
	global_load_dwordx2 v[218:219], v133, s[68:69] offset:288
	s_waitcnt vmcnt(8)
	v_mov_b32_e32 v134, v132
	v_lshlrev_b32_e32 v220, 16, v196
	v_and_b32_e32 v221, 0xffff0000, v196
	v_lshlrev_b32_e32 v222, 16, v197
	v_and_b32_e32 v223, 0xffff0000, v197
	v_pk_fma_f32 v[220:221], v[180:181], v[126:127], v[220:221]
	v_pk_fma_f32 v[222:223], v[182:183], v[128:129], v[222:223]
	v_cvt_pk_bf16_f32 v224, v220, v221
	v_cvt_pk_bf16_f32 v225, v222, v223
	global_store_dwordx2 v134, v[224:225], s[68:69]
	v_lshlrev_b32_e32 v220, 16, v198
	v_and_b32_e32 v221, 0xffff0000, v198
	v_lshlrev_b32_e32 v222, 16, v199
	v_and_b32_e32 v223, 0xffff0000, v199
	v_pk_fma_f32 v[220:221], v[184:185], v[122:123], v[220:221]
	v_pk_fma_f32 v[222:223], v[186:187], v[124:125], v[222:223]
	v_cvt_pk_bf16_f32 v224, v220, v221
	v_cvt_pk_bf16_f32 v225, v222, v223
	global_store_dwordx2 v134, v[224:225], s[68:69] offset:32
	v_lshlrev_b32_e32 v220, 16, v200
	v_and_b32_e32 v221, 0xffff0000, v200
	v_lshlrev_b32_e32 v222, 16, v201
	v_and_b32_e32 v223, 0xffff0000, v201
	v_pk_fma_f32 v[220:221], v[188:189], v[118:119], v[220:221]
	v_pk_fma_f32 v[222:223], v[190:191], v[120:121], v[222:223]
	v_cvt_pk_bf16_f32 v224, v220, v221
	v_cvt_pk_bf16_f32 v225, v222, v223
	global_store_dwordx2 v134, v[224:225], s[68:69] offset:256
	v_lshlrev_b32_e32 v220, 16, v202
	v_and_b32_e32 v221, 0xffff0000, v202
	v_lshlrev_b32_e32 v222, 16, v203
	v_and_b32_e32 v223, 0xffff0000, v203
	v_pk_fma_f32 v[220:221], v[192:193], v[114:115], v[220:221]
	v_pk_fma_f32 v[222:223], v[194:195], v[116:117], v[222:223]
	v_cvt_pk_bf16_f32 v224, v220, v221
	v_cvt_pk_bf16_f32 v225, v222, v223
	global_store_dwordx2 v134, v[224:225], s[68:69] offset:288
	v_add_u32_e32 v133, 0x60000, v132
	global_load_dwordx2 v[196:197], v133, s[68:69]
	global_load_dwordx2 v[198:199], v133, s[68:69] offset:32
	global_load_dwordx2 v[200:201], v133, s[68:69] offset:256
	global_load_dwordx2 v[202:203], v133, s[68:69] offset:288
	s_waitcnt vmcnt(12)
	v_add_u32_e32 v134, 0x20000, v132
	v_lshlrev_b32_e32 v220, 16, v204
	v_and_b32_e32 v221, 0xffff0000, v204
	v_lshlrev_b32_e32 v222, 16, v205
	v_and_b32_e32 v223, 0xffff0000, v205
	v_pk_fma_f32 v[220:221], v[180:181], v[110:111], v[220:221]
	v_pk_fma_f32 v[222:223], v[182:183], v[112:113], v[222:223]
	v_cvt_pk_bf16_f32 v224, v220, v221
	v_cvt_pk_bf16_f32 v225, v222, v223
	global_store_dwordx2 v134, v[224:225], s[68:69]
	v_lshlrev_b32_e32 v220, 16, v206
	v_and_b32_e32 v221, 0xffff0000, v206
	v_lshlrev_b32_e32 v222, 16, v207
	v_and_b32_e32 v223, 0xffff0000, v207
	v_pk_fma_f32 v[220:221], v[184:185], v[106:107], v[220:221]
	v_pk_fma_f32 v[222:223], v[186:187], v[108:109], v[222:223]
	v_cvt_pk_bf16_f32 v224, v220, v221
	v_cvt_pk_bf16_f32 v225, v222, v223
	global_store_dwordx2 v134, v[224:225], s[68:69] offset:32
	v_lshlrev_b32_e32 v220, 16, v208
	v_and_b32_e32 v221, 0xffff0000, v208
	v_lshlrev_b32_e32 v222, 16, v209
	v_and_b32_e32 v223, 0xffff0000, v209
	v_pk_fma_f32 v[220:221], v[188:189], v[102:103], v[220:221]
	v_pk_fma_f32 v[222:223], v[190:191], v[104:105], v[222:223]
	v_cvt_pk_bf16_f32 v224, v220, v221
	v_cvt_pk_bf16_f32 v225, v222, v223
	global_store_dwordx2 v134, v[224:225], s[68:69] offset:256
	v_lshlrev_b32_e32 v220, 16, v210
	v_and_b32_e32 v221, 0xffff0000, v210
	v_lshlrev_b32_e32 v222, 16, v211
	v_and_b32_e32 v223, 0xffff0000, v211
	v_pk_fma_f32 v[220:221], v[192:193], v[98:99], v[220:221]
	v_pk_fma_f32 v[222:223], v[194:195], v[100:101], v[222:223]
	v_cvt_pk_bf16_f32 v224, v220, v221
	v_cvt_pk_bf16_f32 v225, v222, v223
	global_store_dwordx2 v134, v[224:225], s[68:69] offset:288
	v_add_u32_e32 v133, 0x100000, v132
	global_load_dwordx2 v[204:205], v133, s[68:69]
	global_load_dwordx2 v[206:207], v133, s[68:69] offset:32
	global_load_dwordx2 v[208:209], v133, s[68:69] offset:256
	global_load_dwordx2 v[210:211], v133, s[68:69] offset:288
	s_waitcnt vmcnt(16)
;     static __device__ __forceinline__ const void* rowptr(const void* b, size_t r, int ldc) { if constexpr (BASE_BF16) return (const bf16_t*)b + r * ldc; else return (const float*)b + r * ldc; }
;     static __device__ __forceinline__ void stq(bf16_t* p, f32x4 v) { u32x2 w; w.x = cvt_pk_bf16(v[0], v[1]); w.y = cvt_pk_bf16(v[2], v[3]); *(u32x2*)p = w; }
;     __device__ __forceinline__ void operator()(const f32x4 (&acc)[2][2][4][2], const Unit& u, int wr, int wc, int fr, int fq) const {
;     ...
;         if (PIPE && u.pm * BM < split_rows) {
;             f32x4 gq[2][2], bc[2][2], bn[2][2];
;             { const void* rp = rowptr(base_p, (size_t)(u.pm * BM + wr * 64 + fr), ldc);
; #pragma unroll
;             for (int bj = 0; bj < 2; ++bj)
; #pragma unroll
;                 for (int n = 0; n < 2; ++n) { gq[bj][n] = *(const f32x4*)(mod + goff + col0 + bj * HALF + n * 16) * gs; bc[bj][n] = ldb(rp, col0 + bj * HALF + n * 16); } }
; #pragma unroll
;             for (int gi = 0; gi < 8; ++gi) { const int ai = gi >> 2, m = gi & 3; const int r = u.pm * BM + ai * HALF + wr * 64 + m * 16 + fr;
;                 if (gi < 7) { const void* rp = rowptr(base_p, (size_t)(u.pm * BM + ((gi + 1) >> 2) * HALF + wr * 64 + ((gi + 1) & 3) * 16 + fr), ldc);
; #pragma unroll
;                     for (int bj = 0; bj < 2; ++bj)
; #pragma unroll
;                         for (int n = 0; n < 2; ++n) bn[bj][n] = ldb(rp, col0 + bj * HALF + n * 16); }
;                 bf16_t* orow = out + (size_t)r * ldc;
; #pragma unroll
;                 for (int bj = 0; bj < 2; ++bj)
; #pragma unroll
;                     for (int n = 0; n < 2; ++n) { stq(orow + col0 + bj * HALF + n * 16, bc[bj][n] + gq[bj][n] * acc[ai][bj][m][n]); bc[bj][n] = bn[bj][n]; }
;                 asm volatile("" ::: "memory"); }
	v_add_u32_e32 v134, 0x40000, v132
	v_lshlrev_b32_e32 v220, 16, v212
	v_and_b32_e32 v221, 0xffff0000, v212
	v_lshlrev_b32_e32 v222, 16, v213
	v_and_b32_e32 v223, 0xffff0000, v213
	v_pk_fma_f32 v[220:221], v[180:181], v[94:95], v[220:221]
	v_pk_fma_f32 v[222:223], v[182:183], v[96:97], v[222:223]
	v_cvt_pk_bf16_f32 v224, v220, v221
	v_cvt_pk_bf16_f32 v225, v222, v223
	global_store_dwordx2 v134, v[224:225], s[68:69]
	v_lshlrev_b32_e32 v220, 16, v214
	v_and_b32_e32 v221, 0xffff0000, v214
	v_lshlrev_b32_e32 v222, 16, v215
	v_and_b32_e32 v223, 0xffff0000, v215
	v_pk_fma_f32 v[220:221], v[184:185], v[90:91], v[220:221]
	v_pk_fma_f32 v[222:223], v[186:187], v[92:93], v[222:223]
	v_cvt_pk_bf16_f32 v224, v220, v221
	v_cvt_pk_bf16_f32 v225, v222, v223
	global_store_dwordx2 v134, v[224:225], s[68:69] offset:32
	v_lshlrev_b32_e32 v220, 16, v216
	v_and_b32_e32 v221, 0xffff0000, v216
	v_lshlrev_b32_e32 v222, 16, v217
	v_and_b32_e32 v223, 0xffff0000, v217
	v_pk_fma_f32 v[220:221], v[188:189], v[86:87], v[220:221]
	v_pk_fma_f32 v[222:223], v[190:191], v[88:89], v[222:223]
	v_cvt_pk_bf16_f32 v224, v220, v221
	v_cvt_pk_bf16_f32 v225, v222, v223
	global_store_dwordx2 v134, v[224:225], s[68:69] offset:256
	v_lshlrev_b32_e32 v220, 16, v218
	v_and_b32_e32 v221, 0xffff0000, v218
	v_lshlrev_b32_e32 v222, 16, v219
	v_and_b32_e32 v223, 0xffff0000, v219
	v_pk_fma_f32 v[220:221], v[192:193], v[82:83], v[220:221]
	v_pk_fma_f32 v[222:223], v[194:195], v[84:85], v[222:223]
	v_cvt_pk_bf16_f32 v224, v220, v221
	v_cvt_pk_bf16_f32 v225, v222, v223
	global_store_dwordx2 v134, v[224:225], s[68:69] offset:288
	v_add_u32_e32 v133, 0x120000, v132
	global_load_dwordx2 v[212:213], v133, s[68:69]
	global_load_dwordx2 v[214:215], v133, s[68:69] offset:32
	global_load_dwordx2 v[216:217], v133, s[68:69] offset:256
	global_load_dwordx2 v[218:219], v133, s[68:69] offset:288
	s_waitcnt vmcnt(16)
	v_add_u32_e32 v134, 0x60000, v132
	v_lshlrev_b32_e32 v220, 16, v196
	v_and_b32_e32 v221, 0xffff0000, v196
	v_lshlrev_b32_e32 v222, 16, v197
	v_and_b32_e32 v223, 0xffff0000, v197
	v_pk_fma_f32 v[220:221], v[180:181], v[78:79], v[220:221]
	v_pk_fma_f32 v[222:223], v[182:183], v[80:81], v[222:223]
	v_cvt_pk_bf16_f32 v224, v220, v221
	v_cvt_pk_bf16_f32 v225, v222, v223
	global_store_dwordx2 v134, v[224:225], s[68:69]
	v_lshlrev_b32_e32 v220, 16, v198
	v_and_b32_e32 v221, 0xffff0000, v198
	v_lshlrev_b32_e32 v222, 16, v199
	v_and_b32_e32 v223, 0xffff0000, v199
	v_pk_fma_f32 v[220:221], v[184:185], v[74:75], v[220:221]
	v_pk_fma_f32 v[222:223], v[186:187], v[76:77], v[222:223]
	v_cvt_pk_bf16_f32 v224, v220, v221
	v_cvt_pk_bf16_f32 v225, v222, v223
	global_store_dwordx2 v134, v[224:225], s[68:69] offset:32
	v_lshlrev_b32_e32 v220, 16, v200
	v_and_b32_e32 v221, 0xffff0000, v200
	v_lshlrev_b32_e32 v222, 16, v201
	v_and_b32_e32 v223, 0xffff0000, v201
	v_pk_fma_f32 v[220:221], v[188:189], v[70:71], v[220:221]
	v_pk_fma_f32 v[222:223], v[190:191], v[72:73], v[222:223]
	v_cvt_pk_bf16_f32 v224, v220, v221
	v_cvt_pk_bf16_f32 v225, v222, v223
	global_store_dwordx2 v134, v[224:225], s[68:69] offset:256
	v_lshlrev_b32_e32 v220, 16, v202
	v_and_b32_e32 v221, 0xffff0000, v202
	v_lshlrev_b32_e32 v222, 16, v203
	v_and_b32_e32 v223, 0xffff0000, v203
	v_pk_fma_f32 v[220:221], v[192:193], v[66:67], v[220:221]
	v_pk_fma_f32 v[222:223], v[194:195], v[68:69], v[222:223]
	v_cvt_pk_bf16_f32 v224, v220, v221
	v_cvt_pk_bf16_f32 v225, v222, v223
	global_store_dwordx2 v134, v[224:225], s[68:69] offset:288
	v_add_u32_e32 v133, 0x140000, v132
	global_load_dwordx2 v[196:197], v133, s[68:69]
	global_load_dwordx2 v[198:199], v133, s[68:69] offset:32
	global_load_dwordx2 v[200:201], v133, s[68:69] offset:256
	global_load_dwordx2 v[202:203], v133, s[68:69] offset:288
	s_waitcnt vmcnt(16)
	v_add_u32_e32 v134, 0x100000, v132
	v_lshlrev_b32_e32 v220, 16, v204
	v_and_b32_e32 v221, 0xffff0000, v204
	v_lshlrev_b32_e32 v222, 16, v205
	v_and_b32_e32 v223, 0xffff0000, v205
	v_pk_fma_f32 v[220:221], v[180:181], v[62:63], v[220:221]
	v_pk_fma_f32 v[222:223], v[182:183], v[64:65], v[222:223]
	v_cvt_pk_bf16_f32 v224, v220, v221
	v_cvt_pk_bf16_f32 v225, v222, v223
	global_store_dwordx2 v134, v[224:225], s[68:69]
	v_lshlrev_b32_e32 v220, 16, v206
	v_and_b32_e32 v221, 0xffff0000, v206
	v_lshlrev_b32_e32 v222, 16, v207
	v_and_b32_e32 v223, 0xffff0000, v207
	v_pk_fma_f32 v[220:221], v[184:185], v[58:59], v[220:221]
	v_pk_fma_f32 v[222:223], v[186:187], v[60:61], v[222:223]
	v_cvt_pk_bf16_f32 v224, v220, v221
	v_cvt_pk_bf16_f32 v225, v222, v223
	global_store_dwordx2 v134, v[224:225], s[68:69] offset:32
	v_lshlrev_b32_e32 v220, 16, v208
	v_and_b32_e32 v221, 0xffff0000, v208
	v_lshlrev_b32_e32 v222, 16, v209
	v_and_b32_e32 v223, 0xffff0000, v209
	v_pk_fma_f32 v[220:221], v[188:189], v[54:55], v[220:221]
	v_pk_fma_f32 v[222:223], v[190:191], v[56:57], v[222:223]
	v_cvt_pk_bf16_f32 v224, v220, v221
	v_cvt_pk_bf16_f32 v225, v222, v223
	global_store_dwordx2 v134, v[224:225], s[68:69] offset:256
	v_lshlrev_b32_e32 v220, 16, v210
	v_and_b32_e32 v221, 0xffff0000, v210
	v_lshlrev_b32_e32 v222, 16, v211
	v_and_b32_e32 v223, 0xffff0000, v211
	v_pk_fma_f32 v[220:221], v[192:193], v[50:51], v[220:221]
	v_pk_fma_f32 v[222:223], v[194:195], v[52:53], v[222:223]
	v_cvt_pk_bf16_f32 v224, v220, v221
	v_cvt_pk_bf16_f32 v225, v222, v223
	global_store_dwordx2 v134, v[224:225], s[68:69] offset:288
	v_add_u32_e32 v133, 0x160000, v132
	global_load_dwordx2 v[204:205], v133, s[68:69]
	global_load_dwordx2 v[206:207], v133, s[68:69] offset:32
	global_load_dwordx2 v[208:209], v133, s[68:69] offset:256
	global_load_dwordx2 v[210:211], v133, s[68:69] offset:288
	s_waitcnt vmcnt(16)
;     static __device__ __forceinline__ const void* rowptr(const void* b, size_t r, int ldc) { if constexpr (BASE_BF16) return (const bf16_t*)b + r * ldc; else return (const float*)b + r * ldc; }
;     static __device__ __forceinline__ void stq(bf16_t* p, f32x4 v) { u32x2 w; w.x = cvt_pk_bf16(v[0], v[1]); w.y = cvt_pk_bf16(v[2], v[3]); *(u32x2*)p = w; }
;     __device__ __forceinline__ void operator()(const f32x4 (&acc)[2][2][4][2], const Unit& u, int wr, int wc, int fr, int fq) const {
;     ...
;             for (int gi = 0; gi < 8; ++gi) { const int ai = gi >> 2, m = gi & 3; const int r = u.pm * BM + ai * HALF + wr * 64 + m * 16 + fr;
;                 if (gi < 7) { const void* rp = rowptr(base_p, (size_t)(u.pm * BM + ((gi + 1) >> 2) * HALF + wr * 64 + ((gi + 1) & 3) * 16 + fr), ldc);
; #pragma unroll
;                     for (int bj = 0; bj < 2; ++bj)
; #pragma unroll
;                         for (int n = 0; n < 2; ++n) bn[bj][n] = ldb(rp, col0 + bj * HALF + n * 16); }
;                 bf16_t* orow = out + (size_t)r * ldc;
; #pragma unroll
;                 for (int bj = 0; bj < 2; ++bj)
; #pragma unroll
;                     for (int n = 0; n < 2; ++n) { stq(orow + col0 + bj * HALF + n * 16, bc[bj][n] + gq[bj][n] * acc[ai][bj][m][n]); bc[bj][n] = bn[bj][n]; }
;                 asm volatile("" ::: "memory"); }
	v_add_u32_e32 v134, 0x120000, v132
	v_lshlrev_b32_e32 v220, 16, v212
	v_and_b32_e32 v221, 0xffff0000, v212
	v_lshlrev_b32_e32 v222, 16, v213
	v_and_b32_e32 v223, 0xffff0000, v213
	v_pk_fma_f32 v[220:221], v[180:181], v[46:47], v[220:221]
	v_pk_fma_f32 v[222:223], v[182:183], v[48:49], v[222:223]
	v_cvt_pk_bf16_f32 v224, v220, v221
	v_cvt_pk_bf16_f32 v225, v222, v223
	global_store_dwordx2 v134, v[224:225], s[68:69]
	v_lshlrev_b32_e32 v220, 16, v214
	v_and_b32_e32 v221, 0xffff0000, v214
	v_lshlrev_b32_e32 v222, 16, v215
	v_and_b32_e32 v223, 0xffff0000, v215
	v_pk_fma_f32 v[220:221], v[184:185], v[42:43], v[220:221]
	v_pk_fma_f32 v[222:223], v[186:187], v[44:45], v[222:223]
	v_cvt_pk_bf16_f32 v224, v220, v221
	v_cvt_pk_bf16_f32 v225, v222, v223
	global_store_dwordx2 v134, v[224:225], s[68:69] offset:32
	v_lshlrev_b32_e32 v220, 16, v216
	v_and_b32_e32 v221, 0xffff0000, v216
	v_lshlrev_b32_e32 v222, 16, v217
	v_and_b32_e32 v223, 0xffff0000, v217
	v_pk_fma_f32 v[220:221], v[188:189], v[38:39], v[220:221]
	v_pk_fma_f32 v[222:223], v[190:191], v[40:41], v[222:223]
	v_cvt_pk_bf16_f32 v224, v220, v221
	v_cvt_pk_bf16_f32 v225, v222, v223
	global_store_dwordx2 v134, v[224:225], s[68:69] offset:256
	v_lshlrev_b32_e32 v220, 16, v218
	v_and_b32_e32 v221, 0xffff0000, v218
	v_lshlrev_b32_e32 v222, 16, v219
	v_and_b32_e32 v223, 0xffff0000, v219
	v_pk_fma_f32 v[220:221], v[192:193], v[34:35], v[220:221]
	v_pk_fma_f32 v[222:223], v[194:195], v[36:37], v[222:223]
	v_cvt_pk_bf16_f32 v224, v220, v221
	v_cvt_pk_bf16_f32 v225, v222, v223
	global_store_dwordx2 v134, v[224:225], s[68:69] offset:288
	s_waitcnt vmcnt(12)
	v_add_u32_e32 v134, 0x140000, v132
	v_lshlrev_b32_e32 v220, 16, v196
	v_and_b32_e32 v221, 0xffff0000, v196
	v_lshlrev_b32_e32 v222, 16, v197
	v_and_b32_e32 v223, 0xffff0000, v197
	v_pk_fma_f32 v[220:221], v[180:181], v[30:31], v[220:221]
	v_pk_fma_f32 v[222:223], v[182:183], v[32:33], v[222:223]
	v_cvt_pk_bf16_f32 v224, v220, v221
	v_cvt_pk_bf16_f32 v225, v222, v223
	global_store_dwordx2 v134, v[224:225], s[68:69]
	v_lshlrev_b32_e32 v220, 16, v198
	v_and_b32_e32 v221, 0xffff0000, v198
	v_lshlrev_b32_e32 v222, 16, v199
	v_and_b32_e32 v223, 0xffff0000, v199
	v_pk_fma_f32 v[220:221], v[184:185], v[26:27], v[220:221]
	v_pk_fma_f32 v[222:223], v[186:187], v[28:29], v[222:223]
	v_cvt_pk_bf16_f32 v224, v220, v221
	v_cvt_pk_bf16_f32 v225, v222, v223
	global_store_dwordx2 v134, v[224:225], s[68:69] offset:32
	v_lshlrev_b32_e32 v220, 16, v200
	v_and_b32_e32 v221, 0xffff0000, v200
	v_lshlrev_b32_e32 v222, 16, v201
	v_and_b32_e32 v223, 0xffff0000, v201
	v_pk_fma_f32 v[220:221], v[188:189], v[22:23], v[220:221]
	v_pk_fma_f32 v[222:223], v[190:191], v[24:25], v[222:223]
	v_cvt_pk_bf16_f32 v224, v220, v221
	v_cvt_pk_bf16_f32 v225, v222, v223
	global_store_dwordx2 v134, v[224:225], s[68:69] offset:256
	v_lshlrev_b32_e32 v220, 16, v202
	v_and_b32_e32 v221, 0xffff0000, v202
	v_lshlrev_b32_e32 v222, 16, v203
	v_and_b32_e32 v223, 0xffff0000, v203
	v_pk_fma_f32 v[220:221], v[192:193], v[18:19], v[220:221]
	v_pk_fma_f32 v[222:223], v[194:195], v[20:21], v[222:223]
	v_cvt_pk_bf16_f32 v224, v220, v221
	v_cvt_pk_bf16_f32 v225, v222, v223
	global_store_dwordx2 v134, v[224:225], s[68:69] offset:288
	s_waitcnt vmcnt(8)
	v_add_u32_e32 v134, 0x160000, v132
	v_lshlrev_b32_e32 v220, 16, v204
	v_and_b32_e32 v221, 0xffff0000, v204
	v_lshlrev_b32_e32 v222, 16, v205
	v_and_b32_e32 v223, 0xffff0000, v205
	v_pk_fma_f32 v[220:221], v[180:181], v[14:15], v[220:221]
	v_pk_fma_f32 v[222:223], v[182:183], v[16:17], v[222:223]
	v_cvt_pk_bf16_f32 v224, v220, v221
	v_cvt_pk_bf16_f32 v225, v222, v223
	global_store_dwordx2 v134, v[224:225], s[68:69]
	v_lshlrev_b32_e32 v220, 16, v206
	v_and_b32_e32 v221, 0xffff0000, v206
	v_lshlrev_b32_e32 v222, 16, v207
	v_and_b32_e32 v223, 0xffff0000, v207
	v_pk_fma_f32 v[220:221], v[184:185], v[10:11], v[220:221]
	v_pk_fma_f32 v[222:223], v[186:187], v[12:13], v[222:223]
	v_cvt_pk_bf16_f32 v224, v220, v221
	v_cvt_pk_bf16_f32 v225, v222, v223
	global_store_dwordx2 v134, v[224:225], s[68:69] offset:32
	v_lshlrev_b32_e32 v220, 16, v208
	v_and_b32_e32 v221, 0xffff0000, v208
	v_lshlrev_b32_e32 v222, 16, v209
	v_and_b32_e32 v223, 0xffff0000, v209
	v_pk_fma_f32 v[220:221], v[188:189], v[6:7], v[220:221]
	v_pk_fma_f32 v[222:223], v[190:191], v[8:9], v[222:223]
	v_cvt_pk_bf16_f32 v224, v220, v221
	v_cvt_pk_bf16_f32 v225, v222, v223
	global_store_dwordx2 v134, v[224:225], s[68:69] offset:256
	v_lshlrev_b32_e32 v220, 16, v210
	v_and_b32_e32 v221, 0xffff0000, v210
	v_lshlrev_b32_e32 v222, 16, v211
	v_and_b32_e32 v223, 0xffff0000, v211
	v_pk_fma_f32 v[220:221], v[192:193], v[2:3], v[220:221]
	v_pk_fma_f32 v[222:223], v[194:195], v[4:5], v[222:223]
	v_cvt_pk_bf16_f32 v224, v220, v221
	v_cvt_pk_bf16_f32 v225, v222, v223
	global_store_dwordx2 v134, v[224:225], s[68:69] offset:288
	s_andn2_b64 vcc, exec, s[2:3]
	s_mov_b64 s[2:3], -1
	s_cbranch_vccnz .LBB0_721
